# phase G start: redundant wait after the gain-vector preload removed (the first iteration's own wait covers it), one exposed round trip less at phase start; on top of v64
# speedup vs baseline: 1.0044x; 1.0002x over previous
.LBB0_898:
	s_or_b64 exec, exec, s[0:1]
	s_waitcnt lgkmcnt(0)
	v_mov_b32_e32 v0, v182
	s_barrier
	v_readlane_b32 s0, v252, 0
	v_ashrrev_i32_e32 v0, 5, v0
	v_and_b32_e32 v0, -2, v0
	v_lshl_add_u32 v16, s0, 4, v0
	s_movk_i32 s0, 0x4000
	v_cmp_gt_i32_e32 vcc, s0, v16
	s_and_saveexec_b64 s[0:1], vcc
	s_cbranch_execz .LBB0_901
	v_lshlrev_b32_e32 v0, 2, v182
	v_and_b32_e32 v18, 0xfc, v0
	v_mov_b32_e32 v1, 0
	v_lshlrev_b32_e32 v0, 2, v18
	v_lshl_add_u64 v[20:21], s[54:55], 0, v[0:1]
	s_mov_b64 s[0:1], 0x1000
	v_lshl_add_u64 v[22:23], v[20:21], 0, s[0:1]
	s_mov_b64 s[0:1], 0x1400
	v_lshl_add_u64 v[24:25], v[20:21], 0, s[0:1]
	s_mov_b64 s[0:1], 0x1800
	v_lshl_add_u64 v[26:27], v[20:21], 0, s[0:1]
	s_mov_b64 s[0:1], 0x1c00
	s_lshl_b32 s5, s96, 4
	v_lshl_add_u64 v[28:29], v[20:21], 0, s[0:1]
	s_mov_b64 s[2:3], 0
	s_movk_i32 s8, 0x2000
	s_movk_i32 s9, 0x1000
	s_movk_i32 s10, 0x3000
	s_mov_b32 s4, 0x3a000000
	s_mov_b32 s11, 0x800000
	s_movk_i32 s12, 0x3fff
	v_mov_b32_e32 v30, 0x358637bd
	global_load_dwordx4 v[140:143], v[20:21], off
	global_load_dwordx4 v[144:147], v[20:21], off offset:1024
	global_load_dwordx4 v[148:151], v[20:21], off offset:2048
	global_load_dwordx4 v[152:155], v[20:21], off offset:3072
	global_load_dwordx4 v[156:159], v[22:23], off
	global_load_dwordx4 v[160:163], v[24:25], off
	global_load_dwordx4 v[164:167], v[26:27], off
	global_load_dwordx4 v[168:171], v[28:29], off
	s_nop 0
